# v17 without the warm-up dummy loads in the LRU passes (gelu-gate row prefetch kept)
# speedup vs baseline: 1.0048x; 1.0030x over previous
; #define LAS __attribute__((address_space(3)))
; __device__ __forceinline__ unsigned cvt_pk_bf16(float lo, float hi) { unsigned r; asm volatile("v_cvt_pk_bf16_f32 %0, %1, %2" : "=v"(r) : "v"(lo), "v"(hi)); return r; }
; __device__ __forceinline__ float bflo(unsigned w) { return __uint_as_float(w << 16); }
; __device__ __forceinline__ float bfhi(unsigned w) { return __uint_as_float(w & 0xffff0000u); }
; template <int PASS> __device__ __forceinline__ void lru_wave_item(LAS unsigned char* lds, LAS unsigned char* vw, int b, int c, int h, const MixP& p, int lane, float (&Hrun)[8], bool cont) {
;     ...
;         u32x4 ur[7];
;         {
;             const int sb = s0 + 4 * fq - 3;
; #pragma unroll
;             for (int r = 0; r < 7; ++r) ur[r] = *(const u32x4*)(ub + (size_t)max(sb + r, 0) * P1W);
;         }
;         if (s0 == 0 && fq == 0) {
; #pragma unroll
;             for (int r = 0; r < 3; ++r) ur[r] = (u32x4){0u, 0u, 0u, 0u};
;         }
; #pragma unroll
;         for (int jj = 0; jj < 4; ++jj) {
;             f32x2 o[4] = {bv[0], bv[1], bv[2], bv[3]};
; #pragma unroll
;             for (int k = 0; k < 4; ++k) { const u32x4 uk = ur[jj + k];
;                 o[0] = wv[k][0] * (f32x2){bflo(uk.x), bfhi(uk.x)} + o[0]; o[1] = wv[k][1] * (f32x2){bflo(uk.y), bfhi(uk.y)} + o[1];
;                 o[2] = wv[k][2] * (f32x2){bflo(uk.z), bfhi(uk.z)} + o[2]; o[3] = wv[k][3] * (f32x2){bflo(uk.w), bfhi(uk.w)} + o[3]; }
;             { u32x4 w; w.x = cvt_pk_bf16(o[0].x, o[0].y); w.y = cvt_pk_bf16(o[1].x, o[1].y); w.z = cvt_pk_bf16(o[2].x, o[2].y); w.w = cvt_pk_bf16(o[3].x, o[3].y);
;               *(LAS u32x4*)(vw + (4 * fq + jj) * WROW + cg * 16) = w; }
;     ...
;                 const u32x4 g = *(const u32x4*)(p.P2 + row * P2W + h * 128 + cg * 8);
.LBB0_818:
	s_or_b32 s22, s19, s11
	v_add_u32_e32 v0, s22, v224
	v_max_i32_e32 v2, 0, v0
	v_mad_u64_u32 v[2:3], s[20:21], v2, s82, v[182:183]
	global_load_dwordx4 v[74:77], v[2:3], off offset:1024
	v_max_i32_e32 v2, -1, v0
	v_add_u32_e32 v2, 1, v2
	v_mad_u64_u32 v[2:3], s[20:21], v2, s82, v[182:183]
	global_load_dwordx4 v[78:81], v[2:3], off offset:1024
	v_or_b32_e32 v2, 2, v0
	v_max_i32_e32 v2, 0, v2
	v_mad_u64_u32 v[2:3], s[20:21], v2, s82, v[182:183]
	global_load_dwordx4 v[82:85], v[2:3], off offset:1024
	v_or_b32_e32 v2, s22, v223
	v_max_i32_e32 v2, 0, v2
	v_mad_u64_u32 v[2:3], s[20:21], v2, s82, v[182:183]
	global_load_dwordx4 v[70:73], v[2:3], off offset:1024
	v_max_i32_e32 v2, -4, v0
	v_add_u32_e32 v2, 4, v2
	v_mad_u64_u32 v[2:3], s[20:21], v2, s82, v[182:183]
	global_load_dwordx4 v[66:69], v[2:3], off offset:1024
	v_max_i32_e32 v2, -5, v0
	v_add_u32_e32 v2, 5, v2
	v_mad_u64_u32 v[2:3], s[20:21], v2, s82, v[182:183]
	global_load_dwordx4 v[6:9], v[2:3], off offset:1024
	v_max_i32_e32 v0, -6, v0
	v_add_u32_e32 v0, 6, v0
	v_mad_u64_u32 v[2:3], s[20:21], v0, s82, v[182:183]
	global_load_dwordx4 v[2:5], v[2:3], off offset:1024
	s_cmp_eq_u32 s22, 0
	s_cselect_b64 s[20:21], -1, 0
	s_and_b64 s[20:21], s[20:21], s[4:5]
	s_or_b32 s19, s19, s18
	s_and_b64 vcc, exec, s[12:13]
	s_mov_b64 s[12:13], 0
	v_or_b32_e32 v96, s19, v203
	v_mad_i64_i32 v[240:241], s[98:99], v96, s83, v[152:153]
	global_load_dwordx4 v[240:243], v[240:241], off
	v_or_b32_e32 v96, s19, v225
	v_mad_i64_i32 v[244:245], s[98:99], v96, s83, v[152:153]
	global_load_dwordx4 v[244:247], v[244:245], off
	v_or_b32_e32 v96, s19, v226
	v_mad_i64_i32 v[248:249], s[98:99], v96, s83, v[152:153]
	global_load_dwordx4 v[248:251], v[248:249], off
	v_or_b32_e32 v96, s19, v227
	v_mad_i64_i32 v[206:207], s[98:99], v96, s83, v[152:153]
	global_load_dwordx2 v[210:211], v[206:207], off offset:8
	global_load_dwordx2 v[206:207], v[206:207], off
	s_waitcnt vmcnt(11)
	v_cndmask_b32_e64 v0, v77, 0, s[20:21]
	v_cndmask_b32_e64 v77, v75, 0, s[20:21]
	v_cndmask_b32_e64 v75, v74, 0, s[20:21]
	v_cndmask_b32_e64 v86, v76, 0, s[20:21]
	v_lshlrev_b32_e32 v74, 16, v75
	s_waitcnt vmcnt(10)
	v_cndmask_b32_e64 v89, v79, 0, s[20:21]
	v_cndmask_b32_e64 v91, v78, 0, s[20:21]
	v_and_b32_e32 v75, 0xffff0000, v75
	v_lshlrev_b32_e32 v76, 16, v77
	v_and_b32_e32 v77, 0xffff0000, v77
	v_cndmask_b32_e64 v88, v81, 0, s[20:21]
	v_cndmask_b32_e64 v87, v80, 0, s[20:21]
	s_waitcnt vmcnt(9)
	v_cndmask_b32_e64 v102, v83, 0, s[20:21]
	v_cndmask_b32_e64 v98, v82, 0, s[20:21]
	s_waitcnt lgkmcnt(13)
	v_pk_fma_f32 v[74:75], v[26:27], v[74:75], v[58:59]
	v_pk_fma_f32 v[76:77], v[28:29], v[76:77], v[60:61]
	v_lshlrev_b32_e32 v78, 16, v86
	v_and_b32_e32 v79, 0xffff0000, v86
	v_lshlrev_b32_e32 v80, 16, v0
	v_and_b32_e32 v81, 0xffff0000, v0
	v_lshlrev_b32_e32 v90, 16, v91
	v_and_b32_e32 v91, 0xffff0000, v91
	v_lshlrev_b32_e32 v92, 16, v89
	v_and_b32_e32 v93, 0xffff0000, v89
	v_cndmask_b32_e64 v100, v85, 0, s[20:21]
	v_cndmask_b32_e64 v101, v84, 0, s[20:21]
	s_waitcnt lgkmcnt(12)
	v_pk_fma_f32 v[78:79], v[30:31], v[78:79], v[62:63]
	v_pk_fma_f32 v[80:81], v[32:33], v[80:81], v[64:65]
	v_pk_fma_f32 v[82:83], v[34:35], v[90:91], v[74:75]
	v_pk_fma_f32 v[84:85], v[36:37], v[92:93], v[76:77]
	v_lshlrev_b32_e32 v94, 16, v87
	v_and_b32_e32 v95, 0xffff0000, v87
	v_lshlrev_b32_e32 v96, 16, v88
	v_and_b32_e32 v97, 0xffff0000, v88
	v_lshlrev_b32_e32 v74, 16, v98
	v_and_b32_e32 v75, 0xffff0000, v98
	v_lshlrev_b32_e32 v76, 16, v102
	v_and_b32_e32 v77, 0xffff0000, v102
	v_pk_fma_f32 v[86:87], v[38:39], v[94:95], v[78:79]
	v_pk_fma_f32 v[88:89], v[40:41], v[96:97], v[80:81]
	v_pk_fma_f32 v[98:99], v[42:43], v[74:75], v[82:83]
	v_pk_fma_f32 v[84:85], v[44:45], v[76:77], v[84:85]
	v_lshlrev_b32_e32 v78, 16, v101
	v_and_b32_e32 v79, 0xffff0000, v101
	v_lshlrev_b32_e32 v80, 16, v100
	v_and_b32_e32 v81, 0xffff0000, v100
	s_waitcnt vmcnt(8)
	v_lshlrev_b32_e32 v82, 16, v70
	v_and_b32_e32 v83, 0xffff0000, v70
	v_lshlrev_b32_e32 v70, 16, v71
	v_and_b32_e32 v71, 0xffff0000, v71
	v_pk_fma_f32 v[86:87], v[46:47], v[78:79], v[86:87]
	v_pk_fma_f32 v[88:89], v[48:49], v[80:81], v[88:89]
	v_pk_fma_f32 v[100:101], v[52:53], v[70:71], v[84:85]
	v_lshlrev_b32_e32 v84, 16, v72
	v_and_b32_e32 v85, 0xffff0000, v72
	v_lshlrev_b32_e32 v72, 16, v73
	v_and_b32_e32 v73, 0xffff0000, v73
	v_pk_fma_f32 v[98:99], v[50:51], v[82:83], v[98:99]
	v_pk_fma_f32 v[102:103], v[54:55], v[84:85], v[86:87]
	v_pk_fma_f32 v[104:105], v[56:57], v[72:73], v[88:89]
	v_cvt_pk_bf16_f32 v86, v98, v99
	v_cvt_pk_bf16_f32 v87, v100, v101
	v_cvt_pk_bf16_f32 v88, v102, v103
	s_waitcnt vmcnt(7)
	v_lshlrev_b32_e32 v98, 16, v68
	v_cvt_pk_bf16_f32 v89, v104, v105
	ds_write_b128 v229, v[86:89]
	v_pk_fma_f32 v[86:87], v[26:27], v[90:91], v[58:59]
	v_pk_fma_f32 v[88:89], v[28:29], v[92:93], v[60:61]
	v_pk_fma_f32 v[90:91], v[30:31], v[94:95], v[62:63]
	v_pk_fma_f32 v[92:93], v[32:33], v[96:97], v[64:65]
	v_pk_fma_f32 v[86:87], v[34:35], v[74:75], v[86:87]
	v_pk_fma_f32 v[88:89], v[36:37], v[76:77], v[88:89]
	v_pk_fma_f32 v[90:91], v[38:39], v[78:79], v[90:91]
	v_pk_fma_f32 v[92:93], v[40:41], v[80:81], v[92:93]
	v_pk_fma_f32 v[86:87], v[42:43], v[82:83], v[86:87]
	v_pk_fma_f32 v[88:89], v[44:45], v[70:71], v[88:89]
	v_pk_fma_f32 v[90:91], v[46:47], v[84:85], v[90:91]
	v_pk_fma_f32 v[92:93], v[48:49], v[72:73], v[92:93]
	v_lshlrev_b32_e32 v94, 16, v66
	v_and_b32_e32 v95, 0xffff0000, v66
	v_lshlrev_b32_e32 v96, 16, v67
	v_and_b32_e32 v97, 0xffff0000, v67
	v_and_b32_e32 v99, 0xffff0000, v68
	v_lshlrev_b32_e32 v100, 16, v69
	v_and_b32_e32 v101, 0xffff0000, v69
	v_pk_fma_f32 v[86:87], v[50:51], v[94:95], v[86:87]
	v_pk_fma_f32 v[88:89], v[52:53], v[96:97], v[88:89]
	v_pk_fma_f32 v[90:91], v[54:55], v[98:99], v[90:91]
	v_pk_fma_f32 v[92:93], v[56:57], v[100:101], v[92:93]
	v_cvt_pk_bf16_f32 v66, v86, v87
	v_cvt_pk_bf16_f32 v67, v88, v89
	v_cvt_pk_bf16_f32 v68, v90, v91
	s_waitcnt vmcnt(6)
; #define LAS __attribute__((address_space(3)))
; template <int PASS> __device__ __forceinline__ void lru_wave_item(LAS unsigned char* lds, LAS unsigned char* vw, int b, int c, int h, const MixP& p, int lane, float (&Hrun)[8], bool cont) {
;     ...
;         for (int jj = 0; jj < 4; ++jj) {
;             f32x2 o[4] = {bv[0], bv[1], bv[2], bv[3]};
; #pragma unroll
;             for (int k = 0; k < 4; ++k) { const u32x4 uk = ur[jj + k];
;                 o[0] = wv[k][0] * (f32x2){bflo(uk.x), bfhi(uk.x)} + o[0]; o[1] = wv[k][1] * (f32x2){bflo(uk.y), bfhi(uk.y)} + o[1];
;                 o[2] = wv[k][2] * (f32x2){bflo(uk.z), bfhi(uk.z)} + o[2]; o[3] = wv[k][3] * (f32x2){bflo(uk.w), bfhi(uk.w)} + o[3]; }
;             { u32x4 w; w.x = cvt_pk_bf16(o[0].x, o[0].y); w.y = cvt_pk_bf16(o[1].x, o[1].y); w.z = cvt_pk_bf16(o[2].x, o[2].y); w.w = cvt_pk_bf16(o[3].x, o[3].y);
;               *(LAS u32x4*)(vw + (4 * fq + jj) * WROW + cg * 16) = w; }
;         }
;         f32x4 aR[8], aI[8];
;         bf16x8 af[4];
;         {
; #pragma unroll
;             for (int kk = 0; kk < 4; ++kk) af[kk] = *(const LAS bf16x8*)(vw + fr * WROW + kk * 64 + fq * 16);
; #pragma unroll
;             for (int n = 0; n < 8; ++n) {
;                 aR[n] = (f32x4){0.f, 0.f, 0.f, 0.f}; aI[n] = (f32x4){0.f, 0.f, 0.f, 0.f};
; #pragma unroll
;                 for (int kk = 0; kk < 4; ++kk) {
;                     const bf16x8 ba = *(const LAS bf16x8*)(lds + WA_OFF + (16 * n + fr) * WROW + kk * 64 + fq * 16);
;                     const bf16x8 bx = *(const LAS bf16x8*)(lds + WX_OFF + (16 * n + fr) * WROW + kk * 64 + fq * 16);
;                     aR[n] = __builtin_amdgcn_mfma_f32_16x16x32_bf16(af[kk], ba, aR[n], 0, 0, 0);
;                     aI[n] = __builtin_amdgcn_mfma_f32_16x16x32_bf16(af[kk], bx, aI[n], 0, 0, 0);
;                 }
;             }
;         }
; #pragma unroll
;         for (int n = 0; n < 8; ++n) {
;             const f32x4 aVn = __builtin_amdgcn_mfma_f32_16x16x32_bf16(af[n >> 1], idf[n & 1], (f32x4){0.f, 0.f, 0.f, 0.f}, 0, 0, 0);
;             float av[4], bxv[4];
; #pragma unroll
;             for (int j = 0; j < 4; ++j) {
;                 const float r = fsig2(aR[n][j] + pba[n]), ig = fsig2(aI[n][j] + pbx[n]);
;                 const float a = __builtin_amdgcn_exp2f(r * pk8[n]), mult = __builtin_amdgcn_sqrtf(fmaxf(1.0f - a * a, 0.f));
	v_lshlrev_b32_e32 v86, 16, v8
	v_cvt_pk_bf16_f32 v69, v92, v93
	ds_write_b128 v229, v[66:69] offset:272
	v_pk_fma_f32 v[66:67], v[26:27], v[74:75], v[58:59]
	v_pk_fma_f32 v[68:69], v[28:29], v[76:77], v[60:61]
	v_pk_fma_f32 v[74:75], v[30:31], v[78:79], v[62:63]
	v_pk_fma_f32 v[76:77], v[32:33], v[80:81], v[64:65]
	v_pk_fma_f32 v[66:67], v[34:35], v[82:83], v[66:67]
	v_pk_fma_f32 v[68:69], v[36:37], v[70:71], v[68:69]
	v_pk_fma_f32 v[74:75], v[38:39], v[84:85], v[74:75]
	v_pk_fma_f32 v[76:77], v[40:41], v[72:73], v[76:77]
	v_pk_fma_f32 v[66:67], v[42:43], v[94:95], v[66:67]
	v_pk_fma_f32 v[68:69], v[44:45], v[96:97], v[68:69]
	v_pk_fma_f32 v[74:75], v[46:47], v[98:99], v[74:75]
	v_pk_fma_f32 v[76:77], v[48:49], v[100:101], v[76:77]
	v_lshlrev_b32_e32 v78, 16, v6
	v_and_b32_e32 v79, 0xffff0000, v6
	v_lshlrev_b32_e32 v80, 16, v7
	v_and_b32_e32 v81, 0xffff0000, v7
	v_and_b32_e32 v87, 0xffff0000, v8
	v_lshlrev_b32_e32 v88, 16, v9
	v_and_b32_e32 v89, 0xffff0000, v9
	v_pk_fma_f32 v[66:67], v[50:51], v[78:79], v[66:67]
	v_pk_fma_f32 v[68:69], v[52:53], v[80:81], v[68:69]
	v_pk_fma_f32 v[74:75], v[54:55], v[86:87], v[74:75]
	v_pk_fma_f32 v[76:77], v[56:57], v[88:89], v[76:77]
	v_cvt_pk_bf16_f32 v6, v66, v67
	v_cvt_pk_bf16_f32 v7, v68, v69
	v_cvt_pk_bf16_f32 v8, v74, v75
	v_pk_fma_f32 v[66:67], v[30:31], v[84:85], v[62:63]
	v_cvt_pk_bf16_f32 v9, v76, v77
	ds_write_b128 v229, v[6:9] offset:544
	v_pk_fma_f32 v[6:7], v[26:27], v[82:83], v[58:59]
	v_pk_fma_f32 v[8:9], v[28:29], v[70:71], v[60:61]
	v_pk_fma_f32 v[68:69], v[32:33], v[72:73], v[64:65]
	v_pk_fma_f32 v[6:7], v[34:35], v[94:95], v[6:7]
	v_pk_fma_f32 v[8:9], v[36:37], v[96:97], v[8:9]
	v_pk_fma_f32 v[66:67], v[38:39], v[98:99], v[66:67]
	v_pk_fma_f32 v[68:69], v[40:41], v[100:101], v[68:69]
	v_pk_fma_f32 v[6:7], v[42:43], v[78:79], v[6:7]
	v_pk_fma_f32 v[8:9], v[44:45], v[80:81], v[8:9]
	v_pk_fma_f32 v[70:71], v[46:47], v[86:87], v[66:67]
	v_pk_fma_f32 v[66:67], v[48:49], v[88:89], v[68:69]
	s_waitcnt vmcnt(5)
	v_lshlrev_b32_e32 v68, 16, v2
	v_and_b32_e32 v69, 0xffff0000, v2
	v_lshlrev_b32_e32 v2, 16, v3
	v_and_b32_e32 v3, 0xffff0000, v3
	v_pk_fma_f32 v[6:7], v[50:51], v[68:69], v[6:7]
	v_pk_fma_f32 v[2:3], v[52:53], v[2:3], v[8:9]
	v_lshlrev_b32_e32 v8, 16, v4
	v_and_b32_e32 v9, 0xffff0000, v4
	v_lshlrev_b32_e32 v4, 16, v5
	v_and_b32_e32 v5, 0xffff0000, v5
	v_pk_fma_f32 v[8:9], v[54:55], v[8:9], v[70:71]
	v_pk_fma_f32 v[66:67], v[56:57], v[4:5], v[66:67]
	v_cvt_pk_bf16_f32 v4, v6, v7
	v_cvt_pk_bf16_f32 v5, v2, v3
	v_cvt_pk_bf16_f32 v6, v8, v9
	v_and_or_b32 v0, v213, 64, v202
	v_cvt_pk_bf16_f32 v7, v66, v67
	ds_write_b128 v229, v[4:7] offset:816
	ds_read_b128 v[118:121], v230
	ds_read_b128 v[90:93], v230 offset:64
	ds_read_b128 v[6:9], v230 offset:128
	ds_read_b128 v[2:5], v230 offset:192
	ds_read_b128 v[66:69], v231
	ds_read_b128 v[70:73], v231 offset:34816
	ds_read_b128 v[74:77], v231 offset:64
	ds_read_b128 v[78:81], v231 offset:34880
	s_waitcnt lgkmcnt(3)
	v_mfma_f32_16x16x32_bf16 v[66:69], v[118:121], v[66:69], 0
	v_lshlrev_b32_e32 v0, 2, v0
	s_waitcnt lgkmcnt(2)
	v_mfma_f32_16x16x32_bf16 v[70:73], v[118:121], v[70:73], 0
	s_waitcnt lgkmcnt(1)
	v_mfma_f32_16x16x32_bf16 v[66:69], v[90:93], v[74:77], v[66:69]
	s_waitcnt lgkmcnt(0)
	v_mfma_f32_16x16x32_bf16 v[70:73], v[90:93], v[78:81], v[70:73]
	ds_read_b128 v[74:77], v231 offset:128
	ds_read_b128 v[78:81], v231 offset:34944
	s_waitcnt lgkmcnt(1)
	v_mfma_f32_16x16x32_bf16 v[66:69], v[6:9], v[74:77], v[66:69]
	s_waitcnt lgkmcnt(0)
	v_mfma_f32_16x16x32_bf16 v[70:73], v[6:9], v[78:81], v[70:73]
	ds_read_b128 v[74:77], v231 offset:192
	ds_read_b128 v[78:81], v231 offset:35008
	s_waitcnt lgkmcnt(1)
	v_mfma_f32_16x16x32_bf16 v[134:137], v[2:5], v[74:77], v[66:69]
	s_waitcnt lgkmcnt(0)
	v_mfma_f32_16x16x32_bf16 v[130:133], v[2:5], v[78:81], v[70:73]
	s_nop 0
	ds_read_b128 v[66:69], v231 offset:4352
	s_nop 0
	ds_read_b128 v[70:73], v231 offset:39168
	ds_read_b128 v[74:77], v231 offset:4416
	ds_read_b128 v[78:81], v231 offset:39232
	v_add_f32_e32 v134, v158, v134
	s_waitcnt lgkmcnt(3)
	v_mfma_f32_16x16x32_bf16 v[66:69], v[118:121], v[66:69], 0
	v_add_f32_e32 v135, v158, v135
	v_mul_f32_e32 v134, 0xbfb8aa3b, v134
	v_mul_f32_e32 v135, 0xbfb8aa3b, v135
	s_waitcnt lgkmcnt(2)
	v_mfma_f32_16x16x32_bf16 v[70:73], v[118:121], v[70:73], 0
	v_exp_f32_e32 v134, v134
	v_exp_f32_e32 v135, v135
	v_add_f32_e32 v130, v160, v130
	s_waitcnt lgkmcnt(1)
	v_mfma_f32_16x16x32_bf16 v[66:69], v[90:93], v[74:77], v[66:69]
	v_add_f32_e32 v134, 1.0, v134
	v_add_f32_e32 v135, 1.0, v135
	v_rcp_f32_e32 v134, v134
	s_waitcnt lgkmcnt(0)
	v_mfma_f32_16x16x32_bf16 v[70:73], v[90:93], v[78:81], v[70:73]
	ds_read_b128 v[74:77], v231 offset:4480
	ds_read_b128 v[78:81], v231 offset:39296
	v_rcp_f32_e32 v135, v135
	v_mul_f32_e32 v134, v162, v134
	s_waitcnt lgkmcnt(1)
	v_mfma_f32_16x16x32_bf16 v[66:69], v[6:9], v[74:77], v[66:69]
	v_add_f32_e32 v131, v160, v131
	v_mul_f32_e32 v135, v162, v135
	v_mul_f32_e32 v130, 0xbfb8aa3b, v130
	s_waitcnt lgkmcnt(0)
	v_mfma_f32_16x16x32_bf16 v[70:73], v[6:9], v[78:81], v[70:73]
	ds_read_b128 v[74:77], v231 offset:4544
	ds_read_b128 v[78:81], v231 offset:39360
	v_exp_f32_e32 v236, v134
	v_mul_f32_e32 v131, 0xbfb8aa3b, v131
	s_waitcnt lgkmcnt(1)
	v_mfma_f32_16x16x32_bf16 v[126:129], v[2:5], v[74:77], v[66:69]
	v_exp_f32_e32 v130, v130
	v_exp_f32_e32 v131, v131
	v_fma_f32 v134, -v236, v236, 1.0
	s_waitcnt lgkmcnt(0)
	v_mfma_f32_16x16x32_bf16 v[122:125], v[2:5], v[78:81], v[70:73]
	ds_read_b128 v[66:69], v231 offset:8704
	s_nop 1
	ds_read_b128 v[70:73], v231 offset:43520
	ds_read_b128 v[74:77], v231 offset:8768
	ds_read_b128 v[78:81], v231 offset:43584
	v_add_f32_e32 v130, 1.0, v130
	s_waitcnt lgkmcnt(3)
; #define LAS __attribute__((address_space(3)))
; __device__ __forceinline__ float fsig2(float x) { return __builtin_amdgcn_rcpf(1.0f + __builtin_amdgcn_exp2f(-LOG2E * x)); }
; template <int PASS> __device__ __forceinline__ void lru_wave_item(LAS unsigned char* lds, LAS unsigned char* vw, int b, int c, int h, const MixP& p, int lane, float (&Hrun)[8], bool cont) {
;     ...
;             for (int n = 0; n < 8; ++n) {
;                 aR[n] = (f32x4){0.f, 0.f, 0.f, 0.f}; aI[n] = (f32x4){0.f, 0.f, 0.f, 0.f};
; #pragma unroll
;                 for (int kk = 0; kk < 4; ++kk) {
;                     const bf16x8 ba = *(const LAS bf16x8*)(lds + WA_OFF + (16 * n + fr) * WROW + kk * 64 + fq * 16);
;                     const bf16x8 bx = *(const LAS bf16x8*)(lds + WX_OFF + (16 * n + fr) * WROW + kk * 64 + fq * 16);
;                     aR[n] = __builtin_amdgcn_mfma_f32_16x16x32_bf16(af[kk], ba, aR[n], 0, 0, 0);
;                     aI[n] = __builtin_amdgcn_mfma_f32_16x16x32_bf16(af[kk], bx, aI[n], 0, 0, 0);
;                 }
;             }
;         }
; #pragma unroll
;         for (int n = 0; n < 8; ++n) {
;             const f32x4 aVn = __builtin_amdgcn_mfma_f32_16x16x32_bf16(af[n >> 1], idf[n & 1], (f32x4){0.f, 0.f, 0.f, 0.f}, 0, 0, 0);
;             float av[4], bxv[4];
; #pragma unroll
;             for (int j = 0; j < 4; ++j) {
;                 const float r = fsig2(aR[n][j] + pba[n]), ig = fsig2(aI[n][j] + pbx[n]);
;                 const float a = __builtin_amdgcn_exp2f(r * pk8[n]), mult = __builtin_amdgcn_sqrtf(fmaxf(1.0f - a * a, 0.f));
	v_mfma_f32_16x16x32_bf16 v[66:69], v[118:121], v[66:69], 0
	v_max_f32_e32 v134, 0, v134
	v_add_f32_e32 v131, 1.0, v131
	v_rcp_f32_e32 v130, v130
	s_waitcnt lgkmcnt(2)
	v_mfma_f32_16x16x32_bf16 v[70:73], v[118:121], v[70:73], 0
	v_sqrt_f32_e32 v134, v134
	v_rcp_f32_e32 v131, v131
	v_add_f32_e32 v133, v160, v133
	s_waitcnt lgkmcnt(1)
	v_mfma_f32_16x16x32_bf16 v[66:69], v[90:93], v[74:77], v[66:69]
	v_mul_f32_e32 v133, 0xbfb8aa3b, v133
	v_exp_f32_e32 v133, v133
	v_add_f32_e32 v132, v160, v132
	s_waitcnt lgkmcnt(0)
	v_mfma_f32_16x16x32_bf16 v[70:73], v[90:93], v[78:81], v[70:73]
	ds_read_b128 v[74:77], v231 offset:8832
	ds_read_b128 v[78:81], v231 offset:43648
	v_mul_f32_e32 v132, 0xbfb8aa3b, v132
	v_exp_f32_e32 v132, v132
	s_waitcnt lgkmcnt(1)
	v_mfma_f32_16x16x32_bf16 v[66:69], v[6:9], v[74:77], v[66:69]
	v_add_f32_e32 v133, 1.0, v133
	v_add_f32_e32 v132, 1.0, v132
	v_rcp_f32_e32 v132, v132
	s_waitcnt lgkmcnt(0)
	v_mfma_f32_16x16x32_bf16 v[70:73], v[6:9], v[78:81], v[70:73]
	ds_read_b128 v[74:77], v231 offset:8896
	ds_read_b128 v[78:81], v231 offset:43712
	s_waitcnt lgkmcnt(1)
	v_mfma_f32_16x16x32_bf16 v[114:117], v[2:5], v[74:77], v[66:69]
	s_waitcnt lgkmcnt(0)
	v_mfma_f32_16x16x32_bf16 v[110:113], v[2:5], v[78:81], v[70:73]
	s_nop 0
	ds_read_b128 v[66:69], v232
	s_nop 0
	ds_read_b128 v[70:73], v232 offset:34816
	ds_read_b128 v[74:77], v232 offset:64
	ds_read_b128 v[78:81], v232 offset:34880
	s_waitcnt lgkmcnt(3)
	v_mfma_f32_16x16x32_bf16 v[66:69], v[118:121], v[66:69], 0
	s_waitcnt lgkmcnt(2)
	v_mfma_f32_16x16x32_bf16 v[70:73], v[118:121], v[70:73], 0
	s_waitcnt lgkmcnt(1)
	v_mfma_f32_16x16x32_bf16 v[66:69], v[90:93], v[74:77], v[66:69]
	s_waitcnt lgkmcnt(0)
	v_mfma_f32_16x16x32_bf16 v[70:73], v[90:93], v[78:81], v[70:73]
	ds_read_b128 v[74:77], v232 offset:128
	ds_read_b128 v[78:81], v232 offset:34944
	s_waitcnt lgkmcnt(1)
	v_mfma_f32_16x16x32_bf16 v[66:69], v[6:9], v[74:77], v[66:69]
	s_waitcnt lgkmcnt(0)
	v_mfma_f32_16x16x32_bf16 v[70:73], v[6:9], v[78:81], v[70:73]
	ds_read_b128 v[74:77], v232 offset:192
	ds_read_b128 v[78:81], v232 offset:35008
	s_waitcnt lgkmcnt(1)
	v_mfma_f32_16x16x32_bf16 v[106:109], v[2:5], v[74:77], v[66:69]
	s_waitcnt lgkmcnt(0)
	v_mfma_f32_16x16x32_bf16 v[102:105], v[2:5], v[78:81], v[70:73]
	s_nop 0
	ds_read_b128 v[66:69], v231 offset:17408
	s_nop 0
	ds_read_b128 v[70:73], v231 offset:52224
	ds_read_b128 v[74:77], v231 offset:17472
	ds_read_b128 v[78:81], v231 offset:52288
	s_waitcnt lgkmcnt(3)
	v_mfma_f32_16x16x32_bf16 v[66:69], v[118:121], v[66:69], 0
	s_waitcnt lgkmcnt(2)
	v_mfma_f32_16x16x32_bf16 v[70:73], v[118:121], v[70:73], 0
	s_waitcnt lgkmcnt(1)
	v_mfma_f32_16x16x32_bf16 v[66:69], v[90:93], v[74:77], v[66:69]
	s_waitcnt lgkmcnt(0)
	v_mfma_f32_16x16x32_bf16 v[70:73], v[90:93], v[78:81], v[70:73]
	ds_read_b128 v[74:77], v231 offset:17536
	ds_read_b128 v[78:81], v231 offset:52352
	s_waitcnt lgkmcnt(1)
	v_mfma_f32_16x16x32_bf16 v[66:69], v[6:9], v[74:77], v[66:69]
	s_waitcnt lgkmcnt(0)
	v_mfma_f32_16x16x32_bf16 v[70:73], v[6:9], v[78:81], v[70:73]
	ds_read_b128 v[74:77], v231 offset:17600
	ds_read_b128 v[78:81], v231 offset:52416
	s_waitcnt lgkmcnt(1)
	v_mfma_f32_16x16x32_bf16 v[98:101], v[2:5], v[74:77], v[66:69]
	s_waitcnt lgkmcnt(0)
	v_mfma_f32_16x16x32_bf16 v[94:97], v[2:5], v[78:81], v[70:73]
	s_nop 0
	ds_read_b128 v[66:69], v231 offset:21760
	s_nop 0
	ds_read_b128 v[70:73], v231 offset:56576
	ds_read_b128 v[74:77], v231 offset:21824
	ds_read_b128 v[78:81], v231 offset:56640
	s_waitcnt lgkmcnt(3)
	v_mfma_f32_16x16x32_bf16 v[66:69], v[118:121], v[66:69], 0
	s_waitcnt lgkmcnt(2)
	v_mfma_f32_16x16x32_bf16 v[70:73], v[118:121], v[70:73], 0
	s_waitcnt lgkmcnt(1)
	v_mfma_f32_16x16x32_bf16 v[66:69], v[90:93], v[74:77], v[66:69]
	s_waitcnt lgkmcnt(0)
	v_mfma_f32_16x16x32_bf16 v[70:73], v[90:93], v[78:81], v[70:73]
	ds_read_b128 v[74:77], v231 offset:21888
	ds_read_b128 v[78:81], v231 offset:56704
	s_waitcnt lgkmcnt(1)
	v_mfma_f32_16x16x32_bf16 v[66:69], v[6:9], v[74:77], v[66:69]
	s_waitcnt lgkmcnt(0)
	v_mfma_f32_16x16x32_bf16 v[70:73], v[6:9], v[78:81], v[70:73]
	ds_read_b128 v[74:77], v231 offset:21952
	ds_read_b128 v[78:81], v231 offset:56768
	s_waitcnt lgkmcnt(1)
	v_mfma_f32_16x16x32_bf16 v[86:89], v[2:5], v[74:77], v[66:69]
	s_waitcnt lgkmcnt(0)
	v_mfma_f32_16x16x32_bf16 v[82:85], v[2:5], v[78:81], v[70:73]
	s_nop 0
	ds_read_b128 v[66:69], v231 offset:26112
	s_nop 0
	ds_read_b128 v[70:73], v231 offset:60928
	ds_read_b128 v[74:77], v231 offset:26176
	ds_read_b128 v[78:81], v231 offset:60992
	v_add_f32_e32 v86, v171, v86
	s_waitcnt lgkmcnt(3)
	v_mfma_f32_16x16x32_bf16 v[66:69], v[118:121], v[66:69], 0
	v_add_f32_e32 v87, v171, v87
	v_mul_f32_e32 v86, 0xbfb8aa3b, v86
	v_mul_f32_e32 v87, 0xbfb8aa3b, v87
	s_waitcnt lgkmcnt(2)
	v_mfma_f32_16x16x32_bf16 v[70:73], v[118:121], v[70:73], 0
	v_exp_f32_e32 v86, v86
	v_exp_f32_e32 v87, v87
	v_add_f32_e32 v82, v173, v82
	s_waitcnt lgkmcnt(1)
	v_mfma_f32_16x16x32_bf16 v[66:69], v[90:93], v[74:77], v[66:69]
	v_add_f32_e32 v86, 1.0, v86
	v_add_f32_e32 v87, 1.0, v87
	v_rcp_f32_e32 v86, v86
	s_waitcnt lgkmcnt(0)
	v_mfma_f32_16x16x32_bf16 v[70:73], v[90:93], v[78:81], v[70:73]
	ds_read_b128 v[74:77], v231 offset:26240
	ds_read_b128 v[78:81], v231 offset:61056
	v_rcp_f32_e32 v87, v87
	v_mul_f32_e32 v86, v175, v86
	s_waitcnt lgkmcnt(1)
	v_mfma_f32_16x16x32_bf16 v[66:69], v[6:9], v[74:77], v[66:69]
	ds_read_b128 v[74:77], v231 offset:26304
	ds_read_b128 v[138:141], v231 offset:61120
	v_add_f32_e32 v83, v173, v83
	v_mul_f32_e32 v87, v175, v87
	s_waitcnt lgkmcnt(2)
	v_mfma_f32_16x16x32_bf16 v[70:73], v[6:9], v[78:81], v[70:73]
	v_mul_f32_e32 v82, 0xbfb8aa3b, v82
	v_mul_f32_e32 v83, 0xbfb8aa3b, v83
	v_exp_f32_e32 v82, v82
	s_waitcnt lgkmcnt(1)
; __device__ __forceinline__ float fsig2(float x) { return __builtin_amdgcn_rcpf(1.0f + __builtin_amdgcn_exp2f(-LOG2E * x)); }
; template <int PASS> __device__ __forceinline__ void lru_wave_item(LAS unsigned char* lds, LAS unsigned char* vw, int b, int c, int h, const MixP& p, int lane, float (&Hrun)[8], bool cont) {
;     ...
;         for (int n = 0; n < 8; ++n) {
;             const f32x4 aVn = __builtin_amdgcn_mfma_f32_16x16x32_bf16(af[n >> 1], idf[n & 1], (f32x4){0.f, 0.f, 0.f, 0.f}, 0, 0, 0);
;             float av[4], bxv[4];
; #pragma unroll
;             for (int j = 0; j < 4; ++j) {
;                 const float r = fsig2(aR[n][j] + pba[n]), ig = fsig2(aI[n][j] + pbx[n]);
;                 const float a = __builtin_amdgcn_exp2f(r * pk8[n]), mult = __builtin_amdgcn_sqrtf(fmaxf(1.0f - a * a, 0.f));
;                 av[j] = a; bxv[j] = mult * ig * aVn[j];
;             }
;             const float H0 = bxv[0], H1 = av[1] * H0 + bxv[1], H2 = av[2] * H1 + bxv[2], H3 = av[3] * H2 + bxv[3];
;             const float A0 = av[0], A1 = av[1] * A0, A2 = av[2] * A1, A3 = av[3] * A2;
;             float At[4], Ht[4];
; #pragma unroll
;             for (int q = 0; q < 4; ++q) { At[q] = __shfl(A3, fr + 16 * q); Ht[q] = __shfl(H3, fr + 16 * q); }
;             const float c0 = Hrun[n], c1 = At[0] * c0 + Ht[0], c2 = At[1] * c1 + Ht[1], c3 = At[2] * c2 + Ht[2], c4 = At[3] * c3 + Ht[3];
;             Hrun[n] = c4;
	v_mfma_f32_16x16x32_bf16 v[78:81], v[2:5], v[74:77], v[66:69]
	v_exp_f32_e32 v83, v83
	v_add_f32_e32 v85, v173, v85
	v_add_f32_e32 v82, 1.0, v82
	s_waitcnt lgkmcnt(0)
	v_mfma_f32_16x16x32_bf16 v[74:77], v[2:5], v[138:141], v[70:73]
	ds_read_b128 v[66:69], v233
	s_nop 1
	ds_read_b128 v[70:73], v233 offset:34816
	ds_read_b128 v[138:141], v233 offset:64
	ds_read_b128 v[184:187], v233 offset:34880
	v_add_f32_e32 v83, 1.0, v83
	s_waitcnt lgkmcnt(3)
	v_mfma_f32_16x16x32_bf16 v[66:69], v[118:121], v[66:69], 0
	v_rcp_f32_e32 v82, v82
	v_rcp_f32_e32 v83, v83
	v_mul_f32_e32 v85, 0xbfb8aa3b, v85
	s_waitcnt lgkmcnt(2)
	v_mfma_f32_16x16x32_bf16 v[70:73], v[118:121], v[70:73], 0
	v_exp_f32_e32 v85, v85
	s_nop 0
	v_add_f32_e32 v85, 1.0, v85
	s_waitcnt lgkmcnt(1)
	v_mfma_f32_16x16x32_bf16 v[66:69], v[90:93], v[138:141], v[66:69]
	s_waitcnt lgkmcnt(0)
	v_mfma_f32_16x16x32_bf16 v[70:73], v[90:93], v[184:187], v[70:73]
	ds_read_b128 v[138:141], v233 offset:128
	ds_read_b128 v[184:187], v233 offset:34944
	s_waitcnt lgkmcnt(1)
	v_mfma_f32_16x16x32_bf16 v[66:69], v[6:9], v[138:141], v[66:69]
	s_waitcnt lgkmcnt(0)
	v_mfma_f32_16x16x32_bf16 v[138:141], v[6:9], v[184:187], v[70:73]
	s_nop 2
	ds_read_b128 v[70:73], v233 offset:192
	ds_read_b128 v[184:187], v233 offset:35008
	s_waitcnt lgkmcnt(1)
	v_mfma_f32_16x16x32_bf16 v[70:73], v[2:5], v[70:73], v[66:69]
	s_waitcnt lgkmcnt(0)
	v_mfma_f32_16x16x32_bf16 v[66:69], v[2:5], v[184:187], v[138:141]
	v_exp_f32_e32 v186, v135
	s_nop 0
	v_fma_f32 v135, -v186, v186, 1.0
	v_max_f32_e32 v135, 0, v135
	v_sqrt_f32_e32 v135, v135
	v_mfma_f32_16x16x32_bf16 v[138:141], v[118:121], v[18:21], 0
	s_nop 1
	v_add_f32_e32 v66, v179, v66
	v_add_f32_e32 v67, v179, v67
	v_pk_mul_f32 v[130:131], v[130:131], v[134:135]
	v_add_f32_e32 v134, v158, v136
	v_mul_f32_e32 v134, 0xbfb8aa3b, v134
	v_exp_f32_e32 v134, v134
	v_pk_mul_f32 v[130:131], v[130:131], v[138:139]
	v_rcp_f32_e32 v136, v133
	v_mul_f32_e32 v66, 0xbfb8aa3b, v66
	v_add_f32_e32 v134, 1.0, v134
	v_rcp_f32_e32 v134, v134
	v_mul_f32_e32 v67, 0xbfb8aa3b, v67
	v_exp_f32_e32 v66, v66
	v_exp_f32_e32 v67, v67
	v_mul_f32_e32 v134, v162, v134
	v_exp_f32_e32 v139, v134
	v_add_f32_e32 v134, v158, v137
	v_mul_f32_e32 v134, 0xbfb8aa3b, v134
	v_exp_f32_e32 v134, v134
	v_add_f32_e32 v66, 1.0, v66
	v_add_f32_e32 v67, 1.0, v67
	v_rcp_f32_e32 v66, v66
	v_add_f32_e32 v134, 1.0, v134
	v_rcp_f32_e32 v134, v134
	v_rcp_f32_e32 v67, v67
	v_add_f32_e32 v69, v179, v69
	v_mul_f32_e32 v69, 0xbfb8aa3b, v69
	v_mul_f32_e32 v133, v162, v134
	v_exp_f32_e32 v185, v133
	v_fma_f32 v133, v186, v130, v131
	v_fma_f32 v131, -v139, v139, 1.0
	v_max_f32_e32 v131, 0, v131
	v_sqrt_f32_e32 v138, v131
	v_fma_f32 v131, -v185, v185, 1.0
	v_max_f32_e32 v131, 0, v131
	v_sqrt_f32_e32 v184, v131
	v_pk_mul_f32 v[134:135], v[132:133], v[138:139]
	v_mul_f32_e32 v131, v186, v236
	v_fmac_f32_e32 v135, v134, v140
	v_mov_b32_e32 v137, v135
	v_pk_mul_f32 v[136:137], v[136:137], v[184:185]
	v_mul_f32_e32 v132, v139, v131
	v_fmac_f32_e32 v137, v136, v141
	v_mfma_f32_16x16x32_bf16 v[138:141], v[118:121], v[22:25], 0
	v_add_f32_e32 v118, v159, v126
	v_mul_f32_e32 v118, 0xbfb8aa3b, v118
	v_exp_f32_e32 v118, v118
	v_mul_f32_e32 v134, v185, v132
	ds_bpermute_b32 v188, v0, v134
	ds_bpermute_b32 v192, v0, v137
	v_add_f32_e32 v118, 1.0, v118
	v_rcp_f32_e32 v119, v118
	v_add_f32_e32 v118, v161, v122
	v_mul_f32_e32 v118, 0xbfb8aa3b, v118
	v_exp_f32_e32 v118, v118
	v_mul_f32_e32 v119, v163, v119
	v_exp_f32_e32 v136, v119
	v_add_f32_e32 v122, v161, v125
	v_add_f32_e32 v118, 1.0, v118
	v_rcp_f32_e32 v118, v118
	v_fma_f32 v119, -v136, v136, 1.0
	v_max_f32_e32 v119, 0, v119
	v_sqrt_f32_e32 v120, v119
	v_add_f32_e32 v119, v159, v127
	v_mul_f32_e32 v119, 0xbfb8aa3b, v119
	v_exp_f32_e32 v119, v119
	v_mul_f32_e32 v122, 0xbfb8aa3b, v122
	v_exp_f32_e32 v122, v122
	ds_bpermute_b32 v190, v0, v134 offset:64
	v_add_f32_e32 v119, 1.0, v119
	v_rcp_f32_e32 v121, v119
	v_add_f32_e32 v119, v161, v123
	v_mul_f32_e32 v119, 0xbfb8aa3b, v119
	v_exp_f32_e32 v119, v119
	v_mul_f32_e32 v121, v163, v121
	v_exp_f32_e32 v185, v121
	v_add_f32_e32 v122, 1.0, v122
	v_add_f32_e32 v119, 1.0, v119
	v_rcp_f32_e32 v119, v119
	v_fma_f32 v121, -v185, v185, 1.0
	v_max_f32_e32 v121, 0, v121
	v_sqrt_f32_e32 v121, v121
	ds_bpermute_b32 v196, v0, v137 offset:64
	ds_bpermute_b32 v194, v0, v134 offset:128
	ds_bpermute_b32 v198, v0, v137 offset:128
	v_pk_mul_f32 v[118:119], v[118:119], v[120:121]
	v_add_f32_e32 v120, v159, v128
	v_mul_f32_e32 v120, 0xbfb8aa3b, v120
	v_exp_f32_e32 v120, v120
	v_pk_mul_f32 v[118:119], v[118:119], v[138:139]
	ds_bpermute_b32 v186, v0, v137 offset:192
	v_exp_f32_e32 v69, v69
	v_add_f32_e32 v120, 1.0, v120
	v_rcp_f32_e32 v121, v120
	v_add_f32_e32 v120, v161, v124
	v_mul_f32_e32 v120, 0xbfb8aa3b, v120
	v_exp_f32_e32 v120, v120
	v_mul_f32_e32 v121, v163, v121
	v_exp_f32_e32 v127, v121
	v_add_f32_e32 v121, v159, v129
	v_mul_f32_e32 v121, 0xbfb8aa3b, v121
	v_exp_f32_e32 v121, v121
	v_add_f32_e32 v120, 1.0, v120
	v_rcp_f32_e32 v120, v120
	v_rcp_f32_e32 v124, v122
	v_add_f32_e32 v121, 1.0, v121
	v_rcp_f32_e32 v121, v121
	v_add_f32_e32 v69, 1.0, v69
	ds_bpermute_b32 v184, v0, v134 offset:192
	v_mul_f32_e32 v121, v163, v121
	v_exp_f32_e32 v129, v121
	v_fma_f32 v121, v185, v118, v119
	v_fma_f32 v119, -v127, v127, 1.0
	v_max_f32_e32 v119, 0, v119
	v_sqrt_f32_e32 v126, v119
	v_fma_f32 v119, -v129, v129, 1.0
	v_max_f32_e32 v119, 0, v119
	v_sqrt_f32_e32 v128, v119
	v_pk_mul_f32 v[122:123], v[120:121], v[126:127]
	v_mul_f32_e32 v119, v185, v136
	v_fmac_f32_e32 v123, v122, v140
	v_mov_b32_e32 v125, v123
	v_pk_mul_f32 v[124:125], v[124:125], v[128:129]
	v_mul_f32_e32 v120, v127, v119
	v_fmac_f32_e32 v125, v124, v141
	v_mul_f32_e32 v122, v129, v120
	ds_bpermute_b32 v189, v0, v122
	ds_bpermute_b32 v193, v0, v125
	ds_bpermute_b32 v191, v0, v122 offset:64
	ds_bpermute_b32 v197, v0, v125 offset:64
	ds_bpermute_b32 v195, v0, v122 offset:128
	ds_bpermute_b32 v199, v0, v125 offset:128
	s_waitcnt lgkmcnt(4)
; __device__ __forceinline__ float fsig2(float x) { return __builtin_amdgcn_rcpf(1.0f + __builtin_amdgcn_exp2f(-LOG2E * x)); }
; template <int PASS> __device__ __forceinline__ void lru_wave_item(LAS unsigned char* lds, LAS unsigned char* vw, int b, int c, int h, const MixP& p, int lane, float (&Hrun)[8], bool cont) {
;     ...
;         for (int n = 0; n < 8; ++n) {
;             const f32x4 aVn = __builtin_amdgcn_mfma_f32_16x16x32_bf16(af[n >> 1], idf[n & 1], (f32x4){0.f, 0.f, 0.f, 0.f}, 0, 0, 0);
;             float av[4], bxv[4];
; #pragma unroll
;             for (int j = 0; j < 4; ++j) {
;                 const float r = fsig2(aR[n][j] + pba[n]), ig = fsig2(aI[n][j] + pbx[n]);
;                 const float a = __builtin_amdgcn_exp2f(r * pk8[n]), mult = __builtin_amdgcn_sqrtf(fmaxf(1.0f - a * a, 0.f));
;                 av[j] = a; bxv[j] = mult * ig * aVn[j];
;             }
;             const float H0 = bxv[0], H1 = av[1] * H0 + bxv[1], H2 = av[2] * H1 + bxv[2], H3 = av[3] * H2 + bxv[3];
;             const float A0 = av[0], A1 = av[1] * A0, A2 = av[2] * A1, A3 = av[3] * A2;
;             float At[4], Ht[4];
; #pragma unroll
;             for (int q = 0; q < 4; ++q) { At[q] = __shfl(A3, fr + 16 * q); Ht[q] = __shfl(H3, fr + 16 * q); }
;             const float c0 = Hrun[n], c1 = At[0] * c0 + Ht[0], c2 = At[1] * c1 + Ht[1], c3 = At[2] * c2 + Ht[2], c4 = At[3] * c3 + Ht[3];
;             Hrun[n] = c4;
;             if (PASS == 1) Arun[n] *= (At[0] * At[1]) * (At[2] * At[3]);
;             if (PASS == 2) {
;                 const float cin = fq == 0 ? c0 : (fq == 1 ? c1 : (fq == 2 ? c2 : c3));
;                 aR[n][0] = H0 + A0 * cin; aR[n][1] = H1 + A1 * cin; aR[n][2] = H2 + A2 * cin; aR[n][3] = H3 + A3 * cin;
	v_pk_fma_f32 v[128:129], v[10:11], v[188:189], v[192:193]
	ds_bpermute_b32 v187, v0, v125 offset:192
	s_waitcnt lgkmcnt(3)
	v_pk_fma_f32 v[138:139], v[128:129], v[190:191], v[196:197]
	ds_bpermute_b32 v185, v0, v122 offset:192
	s_waitcnt lgkmcnt(2)
	v_pk_fma_f32 v[126:127], v[138:139], v[194:195], v[198:199]
	s_nop 0
	v_cndmask_b32_e64 v124, v126, v138, s[8:9]
	v_cndmask_b32_e64 v124, v124, v128, s[6:7]
	v_cndmask_b32_e64 v10, v124, v10, s[4:5]
	v_fmac_f32_e32 v130, v236, v10
	v_fmac_f32_e32 v133, v131, v10
	v_fmac_f32_e32 v135, v132, v10
	v_fmac_f32_e32 v137, v134, v10
	v_cndmask_b32_e64 v10, v127, v139, s[8:9]
	v_cndmask_b32_e64 v10, v10, v129, s[6:7]
	v_cndmask_b32_e64 v10, v10, v11, s[4:5]
	v_fmac_f32_e32 v118, v136, v10
	v_fmac_f32_e32 v121, v119, v10
	v_fmac_f32_e32 v123, v120, v10
	v_fmac_f32_e32 v125, v122, v10
	v_add_f32_e32 v10, v164, v114
	v_mul_f32_e32 v10, 0xbfb8aa3b, v10
	v_exp_f32_e32 v10, v10
	v_mfma_f32_16x16x32_bf16 v[138:141], v[90:93], v[18:21], 0
	v_add_f32_e32 v10, 1.0, v10
	v_rcp_f32_e32 v11, v10
	v_add_f32_e32 v10, v166, v110
	v_mul_f32_e32 v10, 0xbfb8aa3b, v10
	v_exp_f32_e32 v10, v10
	v_mul_f32_e32 v11, v168, v11
	v_exp_f32_e32 v119, v11
	v_add_f32_e32 v10, 1.0, v10
	v_rcp_f32_e32 v10, v10
	v_fma_f32 v11, -v119, v119, 1.0
	v_max_f32_e32 v11, 0, v11
	v_sqrt_f32_e32 v110, v11
	v_add_f32_e32 v11, v164, v115
	v_mul_f32_e32 v11, 0xbfb8aa3b, v11
	v_exp_f32_e32 v11, v11
	s_nop 0
	v_add_f32_e32 v11, 1.0, v11
	v_rcp_f32_e32 v114, v11
	v_add_f32_e32 v11, v166, v111
	v_mul_f32_e32 v11, 0xbfb8aa3b, v11
	v_exp_f32_e32 v11, v11
	v_mul_f32_e32 v111, v168, v114
	v_exp_f32_e32 v120, v111
	v_add_f32_e32 v11, 1.0, v11
	v_rcp_f32_e32 v11, v11
	v_fma_f32 v111, -v120, v120, 1.0
	v_max_f32_e32 v111, 0, v111
	v_sqrt_f32_e32 v111, v111
	s_nop 0
	v_pk_mul_f32 v[10:11], v[10:11], v[110:111]
	v_add_f32_e32 v110, v164, v116
	v_mul_f32_e32 v110, 0xbfb8aa3b, v110
	v_exp_f32_e32 v110, v110
	v_pk_mul_f32 v[10:11], v[10:11], v[138:139]
	v_add_f32_e32 v110, 1.0, v110
	v_rcp_f32_e32 v111, v110
	v_add_f32_e32 v110, v166, v112
	v_mul_f32_e32 v110, 0xbfb8aa3b, v110
	v_exp_f32_e32 v110, v110
	v_mul_f32_e32 v111, v168, v111
	v_exp_f32_e32 v129, v111
	v_add_f32_e32 v111, v164, v117
	v_mul_f32_e32 v111, 0xbfb8aa3b, v111
	v_exp_f32_e32 v111, v111
	v_add_f32_e32 v112, v166, v113
	v_mul_f32_e32 v112, 0xbfb8aa3b, v112
	v_exp_f32_e32 v112, v112
	v_add_f32_e32 v111, 1.0, v111
	v_rcp_f32_e32 v111, v111
	v_add_f32_e32 v110, 1.0, v110
	v_rcp_f32_e32 v110, v110
	v_add_f32_e32 v112, 1.0, v112
	v_mul_f32_e32 v111, v168, v111
	v_exp_f32_e32 v117, v111
	v_fma_f32 v111, v120, v10, v11
	v_fma_f32 v11, -v129, v129, 1.0
	v_max_f32_e32 v11, 0, v11
	v_sqrt_f32_e32 v128, v11
	v_fma_f32 v11, -v117, v117, 1.0
	v_max_f32_e32 v11, 0, v11
	v_rcp_f32_e32 v114, v112
	v_sqrt_f32_e32 v116, v11
	v_pk_mul_f32 v[112:113], v[110:111], v[128:129]
	v_mul_f32_e32 v11, v120, v119
	v_fmac_f32_e32 v113, v112, v140
	v_mov_b32_e32 v115, v113
	v_pk_mul_f32 v[114:115], v[114:115], v[116:117]
	v_mul_f32_e32 v110, v129, v11
	v_fmac_f32_e32 v115, v114, v141
	v_mfma_f32_16x16x32_bf16 v[138:141], v[90:93], v[22:25], 0
	v_add_f32_e32 v90, v165, v106
	v_mul_f32_e32 v90, 0xbfb8aa3b, v90
	v_exp_f32_e32 v90, v90
	v_mul_f32_e32 v112, v117, v110
	ds_bpermute_b32 v188, v0, v112
	ds_bpermute_b32 v190, v0, v115
	v_add_f32_e32 v90, 1.0, v90
	v_rcp_f32_e32 v91, v90
	v_add_f32_e32 v90, v167, v102
	v_mul_f32_e32 v90, 0xbfb8aa3b, v90
	v_exp_f32_e32 v90, v90
	v_mul_f32_e32 v91, v169, v91
	v_exp_f32_e32 v114, v91
	v_add_f32_e32 v102, v167, v105
	v_add_f32_e32 v90, 1.0, v90
	v_rcp_f32_e32 v90, v90
	v_fma_f32 v91, -v114, v114, 1.0
	v_max_f32_e32 v91, 0, v91
	v_sqrt_f32_e32 v92, v91
	v_add_f32_e32 v91, v165, v107
	v_mul_f32_e32 v91, 0xbfb8aa3b, v91
	v_exp_f32_e32 v91, v91
	v_mul_f32_e32 v102, 0xbfb8aa3b, v102
	v_exp_f32_e32 v102, v102
	ds_bpermute_b32 v192, v0, v112 offset:64
	v_add_f32_e32 v91, 1.0, v91
	v_rcp_f32_e32 v93, v91
	v_add_f32_e32 v91, v167, v103
	v_mul_f32_e32 v91, 0xbfb8aa3b, v91
	v_exp_f32_e32 v91, v91
	v_mul_f32_e32 v93, v169, v93
	v_exp_f32_e32 v117, v93
	v_add_f32_e32 v102, 1.0, v102
	v_add_f32_e32 v91, 1.0, v91
	v_rcp_f32_e32 v91, v91
	v_fma_f32 v93, -v117, v117, 1.0
	v_max_f32_e32 v93, 0, v93
	v_sqrt_f32_e32 v93, v93
	ds_bpermute_b32 v194, v0, v115 offset:64
	ds_bpermute_b32 v196, v0, v112 offset:128
	ds_bpermute_b32 v198, v0, v115 offset:128
	v_pk_mul_f32 v[90:91], v[90:91], v[92:93]
	v_add_f32_e32 v92, v165, v108
	v_mul_f32_e32 v92, 0xbfb8aa3b, v92
	v_exp_f32_e32 v92, v92
	v_pk_mul_f32 v[90:91], v[90:91], v[138:139]
	ds_bpermute_b32 v128, v0, v115 offset:192
	ds_bpermute_b32 v116, v0, v112 offset:192
	v_add_f32_e32 v92, 1.0, v92
	v_rcp_f32_e32 v93, v92
	v_add_f32_e32 v92, v167, v104
	v_mul_f32_e32 v92, 0xbfb8aa3b, v92
	v_exp_f32_e32 v92, v92
	v_mul_f32_e32 v93, v169, v93
	v_exp_f32_e32 v107, v93
	v_add_f32_e32 v93, v165, v109
	v_mul_f32_e32 v93, 0xbfb8aa3b, v93
	v_exp_f32_e32 v93, v93
	v_add_f32_e32 v92, 1.0, v92
	v_rcp_f32_e32 v92, v92
	v_rcp_f32_e32 v104, v102
	v_add_f32_e32 v93, 1.0, v93
	v_rcp_f32_e32 v93, v93
	s_nop 0
	v_mul_f32_e32 v93, v169, v93
	v_exp_f32_e32 v109, v93
	v_fma_f32 v93, v117, v90, v91
	v_fma_f32 v91, -v107, v107, 1.0
	v_max_f32_e32 v91, 0, v91
	v_sqrt_f32_e32 v106, v91
	v_fma_f32 v91, -v109, v109, 1.0
	v_max_f32_e32 v91, 0, v91
	v_sqrt_f32_e32 v108, v91
	v_pk_mul_f32 v[102:103], v[92:93], v[106:107]
	v_mul_f32_e32 v91, v117, v114
	v_fmac_f32_e32 v103, v102, v140
	v_mov_b32_e32 v105, v103
	v_pk_mul_f32 v[104:105], v[104:105], v[108:109]
	v_mul_f32_e32 v92, v107, v91
	v_fmac_f32_e32 v105, v104, v141
	v_mul_f32_e32 v102, v109, v92
	ds_bpermute_b32 v189, v0, v102
	ds_bpermute_b32 v191, v0, v105
	ds_bpermute_b32 v193, v0, v102 offset:64
	ds_bpermute_b32 v195, v0, v105 offset:64
	ds_bpermute_b32 v197, v0, v102 offset:128
	ds_bpermute_b32 v199, v0, v105 offset:128
	s_waitcnt lgkmcnt(4)
; __device__ __forceinline__ float fsig2(float x) { return __builtin_amdgcn_rcpf(1.0f + __builtin_amdgcn_exp2f(-LOG2E * x)); }
; template <int PASS> __device__ __forceinline__ void lru_wave_item(LAS unsigned char* lds, LAS unsigned char* vw, int b, int c, int h, const MixP& p, int lane, float (&Hrun)[8], bool cont) {
;     ...
;         for (int n = 0; n < 8; ++n) {
;             const f32x4 aVn = __builtin_amdgcn_mfma_f32_16x16x32_bf16(af[n >> 1], idf[n & 1], (f32x4){0.f, 0.f, 0.f, 0.f}, 0, 0, 0);
;             float av[4], bxv[4];
; #pragma unroll
;             for (int j = 0; j < 4; ++j) {
;                 const float r = fsig2(aR[n][j] + pba[n]), ig = fsig2(aI[n][j] + pbx[n]);
;                 const float a = __builtin_amdgcn_exp2f(r * pk8[n]), mult = __builtin_amdgcn_sqrtf(fmaxf(1.0f - a * a, 0.f));
;                 av[j] = a; bxv[j] = mult * ig * aVn[j];
;             }
;             const float H0 = bxv[0], H1 = av[1] * H0 + bxv[1], H2 = av[2] * H1 + bxv[2], H3 = av[3] * H2 + bxv[3];
;             const float A0 = av[0], A1 = av[1] * A0, A2 = av[2] * A1, A3 = av[3] * A2;
;             float At[4], Ht[4];
; #pragma unroll
;             for (int q = 0; q < 4; ++q) { At[q] = __shfl(A3, fr + 16 * q); Ht[q] = __shfl(H3, fr + 16 * q); }
;             const float c0 = Hrun[n], c1 = At[0] * c0 + Ht[0], c2 = At[1] * c1 + Ht[1], c3 = At[2] * c2 + Ht[2], c4 = At[3] * c3 + Ht[3];
;             Hrun[n] = c4;
;             if (PASS == 1) Arun[n] *= (At[0] * At[1]) * (At[2] * At[3]);
;             if (PASS == 2) {
;                 const float cin = fq == 0 ? c0 : (fq == 1 ? c1 : (fq == 2 ? c2 : c3));
;                 aR[n][0] = H0 + A0 * cin; aR[n][1] = H1 + A1 * cin; aR[n][2] = H2 + A2 * cin; aR[n][3] = H3 + A3 * cin;
	v_pk_fma_f32 v[108:109], v[12:13], v[188:189], v[190:191]
	ds_bpermute_b32 v129, v0, v105 offset:192
	s_waitcnt lgkmcnt(3)
	v_pk_fma_f32 v[138:139], v[108:109], v[192:193], v[194:195]
	ds_bpermute_b32 v117, v0, v102 offset:192
	s_waitcnt lgkmcnt(2)
	v_pk_fma_f32 v[106:107], v[138:139], v[196:197], v[198:199]
	s_nop 0
	v_cndmask_b32_e64 v104, v106, v138, s[8:9]
	v_cndmask_b32_e64 v104, v104, v108, s[6:7]
	v_cndmask_b32_e64 v12, v104, v12, s[4:5]
	v_fmac_f32_e32 v111, v11, v12
	v_cndmask_b32_e64 v11, v107, v139, s[8:9]
	v_cndmask_b32_e64 v11, v11, v109, s[6:7]
	v_cndmask_b32_e64 v11, v11, v13, s[4:5]
	v_fmac_f32_e32 v90, v114, v11
	v_fmac_f32_e32 v93, v91, v11
	v_fmac_f32_e32 v103, v92, v11
	v_fmac_f32_e32 v105, v102, v11
	v_add_f32_e32 v11, v170, v98
	v_mul_f32_e32 v11, 0xbfb8aa3b, v11
	v_exp_f32_e32 v11, v11
	v_fmac_f32_e32 v10, v119, v12
	v_fmac_f32_e32 v113, v110, v12
	v_fmac_f32_e32 v115, v112, v12
	v_add_f32_e32 v11, 1.0, v11
	v_rcp_f32_e32 v11, v11
	v_add_f32_e32 v12, v172, v94
	v_mul_f32_e32 v12, 0xbfb8aa3b, v12
	v_exp_f32_e32 v12, v12
	v_mul_f32_e32 v11, v174, v11
	v_exp_f32_e32 v11, v11
	v_mfma_f32_16x16x32_bf16 v[138:141], v[6:9], v[18:21], 0
	v_add_f32_e32 v12, 1.0, v12
	v_rcp_f32_e32 v12, v12
	v_fma_f32 v13, -v11, v11, 1.0
	v_max_f32_e32 v13, 0, v13
	v_sqrt_f32_e32 v94, v13
	v_add_f32_e32 v13, v170, v99
	v_mul_f32_e32 v13, 0xbfb8aa3b, v13
	v_exp_f32_e32 v13, v13
	v_mfma_f32_16x16x32_bf16 v[6:9], v[6:9], v[22:25], 0
	v_add_f32_e32 v13, 1.0, v13
	v_rcp_f32_e32 v91, v13
	v_add_f32_e32 v13, v172, v95
	v_mul_f32_e32 v13, 0xbfb8aa3b, v13
	v_exp_f32_e32 v13, v13
	v_mul_f32_e32 v91, v174, v91
	v_exp_f32_e32 v91, v91
	v_add_f32_e32 v13, 1.0, v13
	v_rcp_f32_e32 v13, v13
	v_fma_f32 v92, -v91, v91, 1.0
	v_max_f32_e32 v92, 0, v92
	v_sqrt_f32_e32 v95, v92
	v_add_f32_e32 v92, v170, v100
	v_mul_f32_e32 v92, 0xbfb8aa3b, v92
	v_exp_f32_e32 v92, v92
	v_pk_mul_f32 v[12:13], v[12:13], v[94:95]
	v_add_f32_e32 v95, v172, v97
	v_mul_f32_e32 v95, 0xbfb8aa3b, v95
	v_add_f32_e32 v92, 1.0, v92
	v_rcp_f32_e32 v92, v92
	v_add_f32_e32 v94, v172, v96
	v_exp_f32_e32 v95, v95
	v_mul_f32_e32 v94, 0xbfb8aa3b, v94
	v_mul_f32_e32 v92, v174, v92
	v_exp_f32_e32 v109, v92
	v_exp_f32_e32 v94, v94
	v_pk_mul_f32 v[12:13], v[12:13], v[138:139]
	v_add_f32_e32 v95, 1.0, v95
	v_rcp_f32_e32 v98, v95
	v_fma_f32 v95, v91, v12, v13
	v_fma_f32 v13, -v109, v109, 1.0
	v_add_f32_e32 v94, 1.0, v94
	v_max_f32_e32 v13, 0, v13
	v_rcp_f32_e32 v94, v94
	v_sqrt_f32_e32 v108, v13
	v_add_f32_e32 v92, v170, v101
	v_mul_f32_e32 v92, 0xbfb8aa3b, v92
	v_exp_f32_e32 v92, v92
	v_pk_mul_f32 v[96:97], v[94:95], v[108:109]
	v_exp_f32_e32 v94, v86
	v_fmac_f32_e32 v97, v96, v140
	v_exp_f32_e32 v96, v87
	v_add_f32_e32 v92, 1.0, v92
	v_fma_f32 v86, -v94, v94, 1.0
	v_max_f32_e32 v86, 0, v86
	v_fma_f32 v87, -v96, v96, 1.0
	v_max_f32_e32 v87, 0, v87
	v_sqrt_f32_e32 v86, v86
	v_sqrt_f32_e32 v87, v87
	v_rcp_f32_e32 v92, v92
	v_mov_b32_e32 v99, v97
	v_pk_mul_f32 v[82:83], v[82:83], v[86:87]
	s_nop 0
	v_pk_mul_f32 v[82:83], v[82:83], v[6:7]
	v_add_f32_e32 v6, v171, v88
	v_mul_f32_e32 v6, 0xbfb8aa3b, v6
	v_exp_f32_e32 v6, v6
	v_add_f32_e32 v7, v173, v84
	v_mul_f32_e32 v7, 0xbfb8aa3b, v7
	v_exp_f32_e32 v7, v7
	v_add_f32_e32 v6, 1.0, v6
	v_rcp_f32_e32 v6, v6
	v_mul_f32_e32 v92, v174, v92
	v_add_f32_e32 v7, 1.0, v7
	v_rcp_f32_e32 v84, v7
	v_mul_f32_e32 v6, v175, v6
	v_exp_f32_e32 v7, v6
	v_add_f32_e32 v6, v171, v89
	v_mul_f32_e32 v6, 0xbfb8aa3b, v6
	v_exp_f32_e32 v6, v6
	v_exp_f32_e32 v101, v92
	v_rcp_f32_e32 v88, v85
	v_fma_f32 v85, v96, v82, v83
	v_add_f32_e32 v6, 1.0, v6
	v_rcp_f32_e32 v6, v6
	v_fma_f32 v13, -v101, v101, 1.0
	v_max_f32_e32 v13, 0, v13
	v_sqrt_f32_e32 v100, v13
	v_mul_f32_e32 v6, v175, v6
	v_exp_f32_e32 v197, v6
	v_fma_f32 v6, -v7, v7, 1.0
	v_max_f32_e32 v6, 0, v6
	v_sqrt_f32_e32 v6, v6
	v_mul_f32_e32 v13, v91, v11
	v_mul_f32_e32 v83, v96, v94
	v_pk_mul_f32 v[98:99], v[98:99], v[100:101]
	v_pk_mul_f32 v[86:87], v[84:85], v[6:7]
	v_fma_f32 v6, -v197, v197, 1.0
	v_max_f32_e32 v6, 0, v6
	v_sqrt_f32_e32 v196, v6
	v_fmac_f32_e32 v87, v86, v8
	v_mov_b32_e32 v89, v87
	v_mul_f32_e32 v91, v109, v13
	v_pk_mul_f32 v[88:89], v[88:89], v[196:197]
	v_mul_f32_e32 v84, v7, v83
	v_fmac_f32_e32 v99, v98, v141
	v_mul_f32_e32 v92, v101, v91
	v_fmac_f32_e32 v89, v88, v9
	v_mul_f32_e32 v86, v197, v84
	ds_bpermute_b32 v138, v0, v92
	ds_bpermute_b32 v140, v0, v99
	ds_bpermute_b32 v139, v0, v86
	ds_bpermute_b32 v141, v0, v89
	ds_bpermute_b32 v188, v0, v92 offset:64
	ds_bpermute_b32 v190, v0, v99 offset:64
	ds_bpermute_b32 v189, v0, v86 offset:64
	ds_bpermute_b32 v191, v0, v89 offset:64
	ds_bpermute_b32 v192, v0, v92 offset:128
	ds_bpermute_b32 v194, v0, v99 offset:128
	ds_bpermute_b32 v193, v0, v86 offset:128
	ds_bpermute_b32 v195, v0, v89 offset:128
	s_waitcnt lgkmcnt(8)
	v_pk_fma_f32 v[8:9], v[14:15], v[138:139], v[140:141]
	ds_bpermute_b32 v108, v0, v99 offset:192
	s_waitcnt lgkmcnt(5)
	v_pk_fma_f32 v[138:139], v[8:9], v[188:189], v[190:191]
	ds_bpermute_b32 v109, v0, v89 offset:192
	s_waitcnt lgkmcnt(2)
	v_pk_fma_f32 v[6:7], v[138:139], v[192:193], v[194:195]
	ds_bpermute_b32 v100, v0, v92 offset:192
	v_cndmask_b32_e64 v88, v6, v138, s[8:9]
	v_cndmask_b32_e64 v8, v88, v8, s[6:7]
	v_cndmask_b32_e64 v8, v8, v14, s[4:5]
	v_fmac_f32_e32 v12, v11, v8
	v_fmac_f32_e32 v95, v13, v8
	v_fmac_f32_e32 v97, v91, v8
	v_fmac_f32_e32 v99, v92, v8
	v_cndmask_b32_e64 v8, v7, v139, s[8:9]
	v_cndmask_b32_e64 v8, v8, v9, s[6:7]
	v_cndmask_b32_e64 v8, v8, v15, s[4:5]
	v_fmac_f32_e32 v82, v94, v8
	v_fmac_f32_e32 v85, v83, v8
	v_fmac_f32_e32 v87, v84, v8
	v_fmac_f32_e32 v89, v86, v8
	v_add_f32_e32 v8, v176, v78
	v_mul_f32_e32 v8, 0xbfb8aa3b, v8
	v_exp_f32_e32 v8, v8
	v_mfma_f32_16x16x32_bf16 v[138:141], v[2:5], v[18:21], 0
	ds_bpermute_b32 v101, v0, v86 offset:192
	v_add_f32_e32 v8, 1.0, v8
	v_rcp_f32_e32 v9, v8
	v_add_f32_e32 v8, v178, v74
	v_mul_f32_e32 v8, 0xbfb8aa3b, v8
	v_exp_f32_e32 v8, v8
	v_mul_f32_e32 v9, v180, v9
	v_exp_f32_e32 v11, v9
	v_mfma_f32_16x16x32_bf16 v[2:5], v[2:5], v[22:25], 0
	v_add_f32_e32 v8, 1.0, v8
	v_rcp_f32_e32 v8, v8
	v_fma_f32 v9, -v11, v11, 1.0
	v_max_f32_e32 v9, 0, v9
	v_sqrt_f32_e32 v14, v9
	v_add_f32_e32 v9, v176, v79
	v_mul_f32_e32 v9, 0xbfb8aa3b, v9
	v_exp_f32_e32 v9, v9
	s_waitcnt lgkmcnt(0)
; #define LAS __attribute__((address_space(3)))
; __device__ __forceinline__ unsigned cvt_pk_bf16(float lo, float hi) { unsigned r; asm volatile("v_cvt_pk_bf16_f32 %0, %1, %2" : "=v"(r) : "v"(lo), "v"(hi)); return r; }
; template <int PASS> __device__ __forceinline__ void lru_wave_item(LAS unsigned char* lds, LAS unsigned char* vw, int b, int c, int h, const MixP& p, int lane, float (&Hrun)[8], bool cont) {
;     ...
;         for (int n = 0; n < 8; ++n) {
;             const f32x4 aVn = __builtin_amdgcn_mfma_f32_16x16x32_bf16(af[n >> 1], idf[n & 1], (f32x4){0.f, 0.f, 0.f, 0.f}, 0, 0, 0);
;             float av[4], bxv[4];
; #pragma unroll
;             for (int j = 0; j < 4; ++j) {
;                 const float r = fsig2(aR[n][j] + pba[n]), ig = fsig2(aI[n][j] + pbx[n]);
;                 const float a = __builtin_amdgcn_exp2f(r * pk8[n]), mult = __builtin_amdgcn_sqrtf(fmaxf(1.0f - a * a, 0.f));
;                 av[j] = a; bxv[j] = mult * ig * aVn[j];
;             }
;             const float H0 = bxv[0], H1 = av[1] * H0 + bxv[1], H2 = av[2] * H1 + bxv[2], H3 = av[3] * H2 + bxv[3];
;             const float A0 = av[0], A1 = av[1] * A0, A2 = av[2] * A1, A3 = av[3] * A2;
;             float At[4], Ht[4];
; #pragma unroll
;             for (int q = 0; q < 4; ++q) { At[q] = __shfl(A3, fr + 16 * q); Ht[q] = __shfl(H3, fr + 16 * q); }
;             const float c0 = Hrun[n], c1 = At[0] * c0 + Ht[0], c2 = At[1] * c1 + Ht[1], c3 = At[2] * c2 + Ht[2], c4 = At[3] * c3 + Ht[3];
;             Hrun[n] = c4;
;             if (PASS == 1) Arun[n] *= (At[0] * At[1]) * (At[2] * At[3]);
;             if (PASS == 2) {
;                 const float cin = fq == 0 ? c0 : (fq == 1 ? c1 : (fq == 2 ? c2 : c3));
;                 aR[n][0] = H0 + A0 * cin; aR[n][1] = H1 + A1 * cin; aR[n][2] = H2 + A2 * cin; aR[n][3] = H3 + A3 * cin;
;             }
;         }
;         if (PASS == 2) {
; #pragma unroll
;             for (int n = 0; n < 8; ++n)
; #pragma unroll
;                 for (int j = 0; j < 4; j += 2) { const unsigned w = cvt_pk_bf16(aR[n][j], aR[n][j + 1]);
;                     *(LAS unsigned short*)(vw + (4 * fq + j) * WROW + (16 * n + fr) * 2) = (unsigned short)(w & 0xffffu);
;                     *(LAS unsigned short*)(vw + (4 * fq + j + 1) * WROW + (16 * n + fr) * 2) = (unsigned short)(w >> 16); }
	v_pk_fma_f32 v[6:7], v[6:7], v[100:101], v[108:109]
	v_add_f32_e32 v9, 1.0, v9
	v_rcp_f32_e32 v13, v9
	v_add_f32_e32 v9, v178, v75
	v_mul_f32_e32 v9, 0xbfb8aa3b, v9
	v_exp_f32_e32 v9, v9
	v_mul_f32_e32 v13, v180, v13
	v_exp_f32_e32 v13, v13
	v_add_f32_e32 v75, v178, v77
	v_add_f32_e32 v9, 1.0, v9
	v_rcp_f32_e32 v9, v9
	v_fma_f32 v15, -v13, v13, 1.0
	v_max_f32_e32 v15, 0, v15
	v_sqrt_f32_e32 v15, v15
	v_mul_f32_e32 v75, 0xbfb8aa3b, v75
	v_exp_f32_e32 v75, v75
	v_pk_mul_f32 v[8:9], v[8:9], v[14:15]
	s_nop 0
	v_pk_mul_f32 v[14:15], v[8:9], v[138:139]
	v_add_f32_e32 v8, v176, v80
	v_mul_f32_e32 v8, 0xbfb8aa3b, v8
	v_exp_f32_e32 v8, v8
	v_add_f32_e32 v9, v178, v76
	v_mul_f32_e32 v9, 0xbfb8aa3b, v9
	v_exp_f32_e32 v9, v9
	v_add_f32_e32 v8, 1.0, v8
	v_rcp_f32_e32 v8, v8
	v_add_f32_e32 v75, 1.0, v75
	v_add_f32_e32 v9, 1.0, v9
	v_rcp_f32_e32 v74, v9
	v_mul_f32_e32 v8, v180, v8
	v_exp_f32_e32 v9, v8
	v_add_f32_e32 v8, v176, v81
	v_mul_f32_e32 v8, 0xbfb8aa3b, v8
	v_exp_f32_e32 v8, v8
	v_rcp_f32_e32 v78, v75
	v_fma_f32 v75, v13, v14, v15
	v_mul_f32_e32 v13, v13, v11
	v_add_f32_e32 v8, 1.0, v8
	v_rcp_f32_e32 v8, v8
	v_mul_f32_e32 v15, v9, v13
	v_mul_f32_e32 v8, v180, v8
	v_exp_f32_e32 v81, v8
	v_fma_f32 v8, -v9, v9, 1.0
	v_max_f32_e32 v8, 0, v8
	v_sqrt_f32_e32 v8, v8
	s_nop 0
	v_pk_mul_f32 v[76:77], v[74:75], v[8:9]
	v_add_f32_e32 v9, v177, v70
	v_mul_f32_e32 v9, 0xbfb8aa3b, v9
	v_exp_f32_e32 v9, v9
	v_fmac_f32_e32 v77, v76, v140
	v_fma_f32 v8, -v81, v81, 1.0
	v_max_f32_e32 v8, 0, v8
	v_add_f32_e32 v9, 1.0, v9
	v_rcp_f32_e32 v9, v9
	v_sqrt_f32_e32 v80, v8
	v_mov_b32_e32 v79, v77
	v_mul_f32_e32 v74, v81, v15
	v_mul_f32_e32 v9, v181, v9
	v_exp_f32_e32 v76, v9
	v_pk_mul_f32 v[78:79], v[78:79], v[80:81]
	ds_bpermute_b32 v8, v0, v74
	v_fmac_f32_e32 v79, v78, v141
	v_fma_f32 v9, -v76, v76, 1.0
	v_max_f32_e32 v9, 0, v9
	v_sqrt_f32_e32 v70, v9
	v_add_f32_e32 v9, v177, v71
	v_mul_f32_e32 v9, 0xbfb8aa3b, v9
	v_exp_f32_e32 v9, v9
	ds_bpermute_b32 v80, v0, v79
	ds_bpermute_b32 v138, v0, v74 offset:64
	ds_bpermute_b32 v140, v0, v79 offset:64
	v_add_f32_e32 v9, 1.0, v9
	v_rcp_f32_e32 v9, v9
	ds_bpermute_b32 v188, v0, v74 offset:128
	ds_bpermute_b32 v190, v0, v79 offset:128
	ds_bpermute_b32 v192, v0, v74 offset:192
	v_mul_f32_e32 v9, v181, v9
	v_exp_f32_e32 v9, v9
	ds_bpermute_b32 v194, v0, v79 offset:192
	v_fma_f32 v71, -v9, v9, 1.0
	v_max_f32_e32 v71, 0, v71
	v_sqrt_f32_e32 v71, v71
	s_nop 0
	v_pk_mul_f32 v[66:67], v[66:67], v[70:71]
	s_nop 0
	v_pk_mul_f32 v[66:67], v[66:67], v[2:3]
	v_add_f32_e32 v2, v177, v72
	v_mul_f32_e32 v2, 0xbfb8aa3b, v2
	v_exp_f32_e32 v2, v2
	v_add_f32_e32 v3, v179, v68
	v_mul_f32_e32 v3, 0xbfb8aa3b, v3
	v_exp_f32_e32 v3, v3
	v_add_f32_e32 v2, 1.0, v2
	v_rcp_f32_e32 v2, v2
	v_rcp_f32_e32 v70, v69
	v_add_f32_e32 v3, 1.0, v3
	v_rcp_f32_e32 v68, v3
	v_mul_f32_e32 v2, v181, v2
	v_exp_f32_e32 v3, v2
	v_add_f32_e32 v2, v177, v73
	v_mul_f32_e32 v2, 0xbfb8aa3b, v2
	v_exp_f32_e32 v2, v2
	v_fma_f32 v69, v9, v66, v67
	v_mul_f32_e32 v67, v9, v76
	v_add_f32_e32 v2, 1.0, v2
	v_rcp_f32_e32 v2, v2
	s_nop 0
	v_mul_f32_e32 v2, v181, v2
	v_exp_f32_e32 v73, v2
	v_fma_f32 v2, -v3, v3, 1.0
	v_max_f32_e32 v2, 0, v2
	v_sqrt_f32_e32 v2, v2
	s_nop 0
	v_pk_mul_f32 v[196:197], v[68:69], v[2:3]
	v_fma_f32 v2, -v73, v73, 1.0
	v_max_f32_e32 v2, 0, v2
	v_sqrt_f32_e32 v72, v2
	v_fmac_f32_e32 v197, v196, v4
	v_mov_b32_e32 v71, v197
	v_mul_f32_e32 v68, v3, v67
	v_pk_mul_f32 v[70:71], v[70:71], v[72:73]
	v_pk_fma_f32 v[2:3], v[126:127], v[184:185], v[186:187]
	v_fmac_f32_e32 v71, v70, v5
	v_mul_f32_e32 v70, v73, v68
	ds_bpermute_b32 v9, v0, v70
	ds_bpermute_b32 v81, v0, v71
	ds_bpermute_b32 v139, v0, v70 offset:64
	ds_bpermute_b32 v141, v0, v71 offset:64
	ds_bpermute_b32 v189, v0, v70 offset:128
	ds_bpermute_b32 v191, v0, v71 offset:128
	s_waitcnt lgkmcnt(4)
	v_pk_fma_f32 v[72:73], v[16:17], v[8:9], v[80:81]
	ds_bpermute_b32 v193, v0, v70 offset:192
	s_waitcnt lgkmcnt(3)
	v_pk_fma_f32 v[80:81], v[72:73], v[138:139], v[140:141]
	ds_bpermute_b32 v195, v0, v71 offset:192
	s_waitcnt lgkmcnt(2)
	v_pk_fma_f32 v[138:139], v[80:81], v[188:189], v[190:191]
	v_pk_fma_f32 v[4:5], v[106:107], v[116:117], v[128:129]
	v_cndmask_b32_e64 v0, v138, v80, s[8:9]
	v_cndmask_b32_e64 v0, v0, v72, s[6:7]
	v_cndmask_b32_e64 v0, v0, v16, s[4:5]
	v_fmac_f32_e32 v14, v11, v0
	v_fmac_f32_e32 v75, v13, v0
	v_fmac_f32_e32 v77, v15, v0
	v_fmac_f32_e32 v79, v74, v0
	v_cndmask_b32_e64 v0, v139, v81, s[8:9]
	v_cndmask_b32_e64 v0, v0, v73, s[6:7]
	v_cndmask_b32_e64 v0, v0, v17, s[4:5]
	v_fmac_f32_e32 v66, v76, v0
	v_fmac_f32_e32 v69, v67, v0
	v_fmac_f32_e32 v197, v68, v0
	v_fmac_f32_e32 v71, v70, v0
	v_cvt_pk_bf16_f32 v0, v130, v133
	ds_write_b16 v234, v0
	ds_write_b16_d16_hi v234, v0 offset:272
	v_cvt_pk_bf16_f32 v0, v135, v137
	ds_write_b16 v234, v0 offset:544
	ds_write_b16_d16_hi v234, v0 offset:816
	v_cvt_pk_bf16_f32 v0, v118, v121
	ds_write_b16 v234, v0 offset:32
	ds_write_b16_d16_hi v234, v0 offset:304
	v_cvt_pk_bf16_f32 v0, v123, v125
	ds_write_b16 v234, v0 offset:576
	ds_write_b16_d16_hi v234, v0 offset:848
	v_cvt_pk_bf16_f32 v0, v10, v111
	ds_write_b16 v234, v0 offset:64
	ds_write_b16_d16_hi v234, v0 offset:336
	v_cvt_pk_bf16_f32 v0, v113, v115
	ds_write_b16 v234, v0 offset:608
	ds_write_b16_d16_hi v234, v0 offset:880
	v_cvt_pk_bf16_f32 v0, v90, v93
	ds_write_b16 v234, v0 offset:96
	ds_write_b16_d16_hi v234, v0 offset:368
	v_cvt_pk_bf16_f32 v0, v103, v105
	ds_write_b16 v234, v0 offset:640
	ds_write_b16_d16_hi v234, v0 offset:912
	v_cvt_pk_bf16_f32 v0, v12, v95
	ds_write_b16 v234, v0 offset:128
	ds_write_b16_d16_hi v234, v0 offset:400
	v_cvt_pk_bf16_f32 v0, v97, v99
	ds_write_b16 v234, v0 offset:672
	ds_write_b16_d16_hi v234, v0 offset:944
	v_cvt_pk_bf16_f32 v0, v82, v85
	ds_write_b16 v234, v0 offset:160
	ds_write_b16_d16_hi v234, v0 offset:432
	v_cvt_pk_bf16_f32 v0, v87, v89
	ds_write_b16 v234, v0 offset:704
	ds_write_b16_d16_hi v234, v0 offset:976
	v_cvt_pk_bf16_f32 v0, v14, v75
	ds_write_b16 v234, v0 offset:192
	ds_write_b16_d16_hi v234, v0 offset:464
	v_cvt_pk_bf16_f32 v0, v77, v79
	ds_write_b16 v234, v0 offset:736
	ds_write_b16_d16_hi v234, v0 offset:1008
	v_cvt_pk_bf16_f32 v0, v66, v69
	ds_write_b16 v234, v0 offset:224
	ds_write_b16_d16_hi v234, v0 offset:496
	v_cvt_pk_bf16_f32 v0, v197, v71
	ds_write_b16 v234, v0 offset:768
	ds_write_b16_d16_hi v234, v0 offset:1040
	v_or_b32_e32 v0, s19, v203
	ds_read_b128 v[10:13], v235
	s_waitcnt lgkmcnt(14)
; #define LAS __attribute__((address_space(3)))
; __device__ __forceinline__ float bflo(unsigned w) { return __uint_as_float(w << 16); }
; __device__ __forceinline__ float bfhi(unsigned w) { return __uint_as_float(w & 0xffff0000u); }
; __device__ __forceinline__ u32x4 pack8(const f32x4 a, const f32x4 b) { u32x4 w; w.x = cvt_pk_bf16(a[0], a[1]); w.y = cvt_pk_bf16(a[2], a[3]); w.z = cvt_pk_bf16(b[0], b[1]); w.w = cvt_pk_bf16(b[2], b[3]); return w; }
; template <int PASS> __device__ __forceinline__ void lru_wave_item(LAS unsigned char* lds, LAS unsigned char* vw, int b, int c, int h, const MixP& p, int lane, float (&Hrun)[8], bool cont) {
;     ...
;             for (int i = 0; i < 4; ++i) {
;                 const int t = fq + 4 * i; const size_t row = (size_t)(row0 + 16 * st + t);
;                 const u32x4 hh = *(const LAS u32x4*)(vw + t * WROW + cg * 16);
;                 const u32x4 g = *(const u32x4*)(p.P2 + row * P2W + h * 128 + cg * 8);
;                 const f32x4 o0 = (f32x4){bflo(hh.x) * bflo(g.x), bfhi(hh.x) * bfhi(g.x), bflo(hh.y) * bflo(g.y), bfhi(hh.y) * bfhi(g.y)};
;                 const f32x4 o1 = (f32x4){bflo(hh.z) * bflo(g.z), bfhi(hh.z) * bfhi(g.z), bflo(hh.w) * bflo(g.w), bfhi(hh.w) * bfhi(g.w)};
;                 *(u32x4*)(p.hl + row * LW + h * 128 + cg * 8) = pack8(o0, o1);
;             }
	v_pk_fma_f32 v[8:9], v[138:139], v[192:193], v[194:195]
	s_waitcnt lgkmcnt(0)
	v_lshlrev_b32_e32 v67, 16, v10
	v_and_b32_e32 v10, 0xffff0000, v10
	s_waitcnt vmcnt(4)
	v_lshlrev_b32_e32 v66, 16, v240
	v_and_b32_e32 v240, 0xffff0000, v240
	v_mul_f32_e32 v66, v66, v67
	v_mul_f32_e32 v10, v240, v10
	v_lshlrev_b32_e32 v240, 16, v241
	v_lshlrev_b32_e32 v67, 16, v11
	v_and_b32_e32 v241, 0xffff0000, v241
	v_and_b32_e32 v11, 0xffff0000, v11
	v_mul_f32_e32 v240, v240, v67
	v_mul_f32_e32 v11, v241, v11
	v_lshlrev_b32_e32 v241, 16, v242
	v_lshlrev_b32_e32 v67, 16, v12
	v_and_b32_e32 v242, 0xffff0000, v242
	v_and_b32_e32 v12, 0xffff0000, v12
	v_mul_f32_e32 v241, v241, v67
	v_mul_f32_e32 v12, v242, v12
	v_lshlrev_b32_e32 v242, 16, v243
	v_lshlrev_b32_e32 v67, 16, v13
	v_and_b32_e32 v243, 0xffff0000, v243
	v_and_b32_e32 v13, 0xffff0000, v13
	v_mul_f32_e32 v13, v243, v13
	v_cvt_pk_bf16_f32 v10, v66, v10
	v_cvt_pk_bf16_f32 v11, v240, v11
	v_cvt_pk_bf16_f32 v12, v241, v12
	v_mad_i64_i32 v[14:15], s[20:21], v0, s40, v[154:155]
	v_or_b32_e32 v0, s19, v225
	v_mul_f32_e32 v242, v242, v67
	v_cvt_pk_bf16_f32 v13, v242, v13
	global_store_dwordx4 v[14:15], v[10:13], off sc1
	ds_read_b128 v[10:13], v235 offset:1088
	s_waitcnt lgkmcnt(0)
	v_lshlrev_b32_e32 v66, 16, v10
	v_and_b32_e32 v10, 0xffff0000, v10
	s_waitcnt vmcnt(4)
	v_lshlrev_b32_e32 v67, 16, v244
	v_and_b32_e32 v244, 0xffff0000, v244
	v_mul_f32_e32 v66, v67, v66
	v_mul_f32_e32 v10, v244, v10
	v_lshlrev_b32_e32 v244, 16, v11
	v_lshlrev_b32_e32 v67, 16, v245
	v_and_b32_e32 v245, 0xffff0000, v245
	v_and_b32_e32 v11, 0xffff0000, v11
	v_mul_f32_e32 v244, v67, v244
	v_mul_f32_e32 v11, v245, v11
	v_lshlrev_b32_e32 v245, 16, v12
	v_lshlrev_b32_e32 v67, 16, v246
	v_and_b32_e32 v246, 0xffff0000, v246
	v_and_b32_e32 v12, 0xffff0000, v12
	v_mul_f32_e32 v245, v67, v245
	v_mul_f32_e32 v12, v246, v12
	v_lshlrev_b32_e32 v246, 16, v13
	v_lshlrev_b32_e32 v67, 16, v247
	v_and_b32_e32 v247, 0xffff0000, v247
	v_and_b32_e32 v13, 0xffff0000, v13
	v_mul_f32_e32 v13, v247, v13
	v_cvt_pk_bf16_f32 v10, v66, v10
	v_cvt_pk_bf16_f32 v11, v244, v11
	v_cvt_pk_bf16_f32 v12, v245, v12
	v_mad_i64_i32 v[14:15], s[20:21], v0, s40, v[154:155]
	v_or_b32_e32 v0, s19, v226
	v_mul_f32_e32 v246, v67, v246
	v_cvt_pk_bf16_f32 v13, v246, v13
	global_store_dwordx4 v[14:15], v[10:13], off sc1
	ds_read_b128 v[10:13], v235 offset:2176
	s_waitcnt lgkmcnt(0)
	v_lshlrev_b32_e32 v66, 16, v10
	v_and_b32_e32 v10, 0xffff0000, v10
	s_waitcnt vmcnt(4)
	v_lshlrev_b32_e32 v67, 16, v248
	v_and_b32_e32 v248, 0xffff0000, v248
	v_mul_f32_e32 v66, v67, v66
	v_mul_f32_e32 v10, v248, v10
	v_lshlrev_b32_e32 v248, 16, v11
	v_lshlrev_b32_e32 v67, 16, v249
	v_and_b32_e32 v249, 0xffff0000, v249
	v_and_b32_e32 v11, 0xffff0000, v11
	v_mul_f32_e32 v248, v67, v248
	v_mul_f32_e32 v11, v249, v11
	v_lshlrev_b32_e32 v249, 16, v12
	v_lshlrev_b32_e32 v67, 16, v250
	v_and_b32_e32 v250, 0xffff0000, v250
	v_and_b32_e32 v12, 0xffff0000, v12
	v_mul_f32_e32 v249, v67, v249
	v_mul_f32_e32 v12, v250, v12
	v_lshlrev_b32_e32 v250, 16, v13
	v_lshlrev_b32_e32 v67, 16, v251
	v_and_b32_e32 v251, 0xffff0000, v251
	v_and_b32_e32 v13, 0xffff0000, v13
	v_mul_f32_e32 v13, v251, v13
	v_cvt_pk_bf16_f32 v10, v66, v10
	v_cvt_pk_bf16_f32 v11, v248, v11
	v_cvt_pk_bf16_f32 v12, v249, v12
	v_mad_i64_i32 v[14:15], s[20:21], v0, s40, v[154:155]
	v_or_b32_e32 v0, s19, v227
	v_mul_f32_e32 v250, v67, v250
	v_cvt_pk_bf16_f32 v13, v250, v13
	global_store_dwordx4 v[14:15], v[10:13], off sc1
	ds_read_b128 v[10:13], v235 offset:3264
	s_mov_b32 s19, 16
	s_waitcnt lgkmcnt(0)
	v_lshlrev_b32_e32 v66, 16, v10
	v_and_b32_e32 v10, 0xffff0000, v10
	s_waitcnt vmcnt(3)
	v_lshlrev_b32_e32 v67, 16, v206
	v_and_b32_e32 v206, 0xffff0000, v206
	v_mul_f32_e32 v66, v67, v66
	v_mul_f32_e32 v10, v206, v10
	v_lshlrev_b32_e32 v206, 16, v11
	v_lshlrev_b32_e32 v67, 16, v207
	v_and_b32_e32 v207, 0xffff0000, v207
	v_and_b32_e32 v11, 0xffff0000, v11
	v_mul_f32_e32 v206, v67, v206
	v_mul_f32_e32 v11, v207, v11
	v_lshlrev_b32_e32 v207, 16, v12
	v_lshlrev_b32_e32 v67, 16, v210
	v_and_b32_e32 v210, 0xffff0000, v210
	v_and_b32_e32 v12, 0xffff0000, v12
	v_mul_f32_e32 v207, v67, v207
	v_mul_f32_e32 v12, v210, v12
	v_lshlrev_b32_e32 v210, 16, v13
	v_lshlrev_b32_e32 v67, 16, v211
	v_and_b32_e32 v211, 0xffff0000, v211
	v_and_b32_e32 v13, 0xffff0000, v13
	v_mul_f32_e32 v13, v211, v13
	v_mul_f32_e32 v210, v67, v210
	v_cvt_pk_bf16_f32 v10, v66, v10
	v_cvt_pk_bf16_f32 v11, v206, v11
	v_cvt_pk_bf16_f32 v12, v207, v12
	v_cvt_pk_bf16_f32 v13, v210, v13
	v_mad_i64_i32 v[14:15], s[20:21], v0, s40, v[154:155]
	global_store_dwordx4 v[14:15], v[10:13], off sc1
	v_mov_b64_e32 v[16:17], v[8:9]
	v_mov_b64_e32 v[14:15], v[6:7]
	v_mov_b64_e32 v[12:13], v[4:5]
	v_mov_b64_e32 v[10:11], v[2:3]
	s_cbranch_vccnz .LBB0_818
	s_add_i32 s1, s1, 1
	s_cmp_ge_i32 s1, s10
	s_cbranch_scc0 .LBB0_811
	s_branch .LBB0_797
